# flip period 4 variant (priorities alternate every 4 MFMA groups)
# baseline (speedup 1.0000x reference)
.Lan_331_h0:
	v_cvt_f32_i32_e32 v237, v231
	s_setprio 1
	s_waitcnt lgkmcnt(4)
	v_mfma_f32_32x32x16_bf16 v[96:111], v[64:67], v[112:115], v[96:111]
	ds_read_b128 v[244:247], v234 offset:34848
	v_exp_f32_e32 v80, v80
	v_exp_f32_e32 v81, v81
	v_add_f32_e32 v238, 0, v80
	v_add_f32_e32 v238, v238, v81
	s_waitcnt lgkmcnt(4)
	v_mfma_f32_32x32x16_bf16 v[96:111], v[68:71], v[116:119], v[96:111]
	ds_read_b128 v[64:67], v234 offset:39424
	v_exp_f32_e32 v82, v82
	v_exp_f32_e32 v83, v83
	v_add_f32_e32 v238, v238, v82
	v_add_f32_e32 v238, v238, v83
	s_waitcnt lgkmcnt(4)
	v_mfma_f32_32x32x16_bf16 v[96:111], v[72:75], v[120:123], v[96:111]
	ds_read_b128 v[68:71], v234 offset:39456
	v_exp_f32_e32 v84, v84
	v_exp_f32_e32 v85, v85
	v_add_f32_e32 v238, v238, v84
	v_add_f32_e32 v238, v238, v85
	s_waitcnt lgkmcnt(4)
	v_mfma_f32_32x32x16_bf16 v[96:111], v[76:79], v[124:127], v[96:111]
	ds_read_b128 v[72:75], v234 offset:44032
	v_exp_f32_e32 v86, v86
	v_exp_f32_e32 v87, v87
	v_add_f32_e32 v238, v238, v86
	v_add_f32_e32 v238, v238, v87
	s_setprio 0
	s_waitcnt lgkmcnt(4)
	v_mfma_f32_32x32x16_bf16 v[48:63], v[160:163], v[144:147], v[48:63]
	ds_read_b128 v[76:79], v234 offset:44064
	v_cvt_pk_bf16_f32 v152, v80, v81
	v_cvt_pk_bf16_f32 v153, v82, v83
	v_cvt_pk_bf16_f32 v154, v84, v85
	v_cvt_pk_bf16_f32 v155, v86, v87
	v_add_f32_e32 v255, 0x42800000, v237
	v_fma_f32 v254, v236, v255, v253
	s_waitcnt lgkmcnt(4)
	v_mfma_f32_32x32x16_bf16 v[48:63], v[244:247], v[148:151], v[48:63]
	ds_read_b128 v[160:163], v234 offset:48640
	v_exp_f32_e32 v88, v88
	v_exp_f32_e32 v89, v89
	v_add_f32_e32 v238, v238, v88
	v_add_f32_e32 v238, v238, v89
	v_fmamk_f32 v80, v201, 0x42000000, v254
	v_fmamk_f32 v81, v201, 0x42040000, v254
	s_waitcnt lgkmcnt(4)
	v_mfma_f32_32x32x16_bf16 v[32:47], v[64:67], v[144:147], v[32:47]
	ds_read_b128 v[244:247], v234 offset:48672
	v_exp_f32_e32 v90, v90
	v_exp_f32_e32 v91, v91
	v_add_f32_e32 v238, v238, v90
	v_add_f32_e32 v238, v238, v91
	v_fmamk_f32 v82, v201, 0x42080000, v254
	v_fmamk_f32 v83, v201, 0x420c0000, v254
	s_waitcnt lgkmcnt(4)
	v_mfma_f32_32x32x16_bf16 v[32:47], v[68:71], v[148:151], v[32:47]
	ds_read_b128 v[64:67], v235 offset:8704
	v_exp_f32_e32 v92, v92
	v_exp_f32_e32 v93, v93
	v_add_f32_e32 v238, v238, v92
	v_add_f32_e32 v238, v238, v93
	v_fmamk_f32 v84, v201, 0x42100000, v254
	v_fmamk_f32 v85, v201, 0x42140000, v254
	s_setprio 1
	s_waitcnt lgkmcnt(4)
	v_mfma_f32_32x32x16_bf16 v[16:31], v[72:75], v[144:147], v[16:31]
	ds_read_b128 v[68:71], v235 offset:8736
	v_exp_f32_e32 v94, v94
	v_exp_f32_e32 v95, v95
	v_add_f32_e32 v238, v238, v94
	v_add_f32_e32 v238, v238, v95
	v_fmamk_f32 v86, v201, 0x42180000, v254
	v_fmamk_f32 v87, v201, 0x421c0000, v254
	s_waitcnt lgkmcnt(4)
	v_mfma_f32_32x32x16_bf16 v[16:31], v[76:79], v[148:151], v[16:31]
	ds_read_b128 v[72:75], v235 offset:8768
	v_cvt_pk_bf16_f32 v156, v88, v89
	v_cvt_pk_bf16_f32 v157, v90, v91
	v_cvt_pk_bf16_f32 v158, v92, v93
	v_cvt_pk_bf16_f32 v159, v94, v95
	s_waitcnt lgkmcnt(4)
	v_mfma_f32_32x32x16_bf16 v[0:15], v[160:163], v[144:147], v[0:15]
	ds_read_b128 v[76:79], v235 offset:8800
	v_fmamk_f32 v88, v201, 0x42400000, v254
	v_fmamk_f32 v89, v201, 0x42440000, v254
	v_fmamk_f32 v90, v201, 0x42480000, v254
	v_fmamk_f32 v91, v201, 0x424c0000, v254
	v_add_f32_e32 v238, v238, v233
	s_waitcnt lgkmcnt(4)
	v_mfma_f32_32x32x16_bf16 v[0:15], v[244:247], v[148:151], v[0:15]
	ds_read_b128 v[160:163], v234 offset:34880
	v_fmamk_f32 v92, v201, 0x42500000, v254
	v_fmamk_f32 v93, v201, 0x42540000, v254
	v_fmamk_f32 v94, v201, 0x42580000, v254
	v_fmamk_f32 v95, v201, 0x425c0000, v254
	s_cmp_lt_u32 s90, 2
	s_cbranch_scc1 .LfixA_skip_h0_do
	s_cmp_lt_i32 s90, s38
	s_cbranch_scc1 .LfixA_skip_h0

.LfixA_skip_h0:
	s_setprio 0
	s_waitcnt lgkmcnt(4)
	v_mfma_f32_32x32x16_bf16 v[80:95], v[64:67], v[112:115], v[80:95]
	ds_read_b128 v[244:247], v234 offset:34912
	v_exp_f32_e32 v96, v96
	v_exp_f32_e32 v97, v97
	v_add_f32_e32 v233, 0, v96
	v_add_f32_e32 v233, v233, v97
	s_waitcnt lgkmcnt(4)
	v_mfma_f32_32x32x16_bf16 v[80:95], v[68:71], v[116:119], v[80:95]
	ds_read_b128 v[64:67], v234 offset:39488
	v_exp_f32_e32 v98, v98
	v_exp_f32_e32 v99, v99
	v_add_f32_e32 v233, v233, v98
	v_add_f32_e32 v233, v233, v99
	s_waitcnt lgkmcnt(4)
	v_mfma_f32_32x32x16_bf16 v[80:95], v[72:75], v[120:123], v[80:95]
	ds_read_b128 v[68:71], v234 offset:39520
	v_exp_f32_e32 v100, v100
	v_exp_f32_e32 v101, v101
	v_add_f32_e32 v233, v233, v100
	v_add_f32_e32 v233, v233, v101
	s_waitcnt lgkmcnt(4)
	v_mfma_f32_32x32x16_bf16 v[80:95], v[76:79], v[124:127], v[80:95]
	ds_read_b128 v[72:75], v234 offset:44096
	v_exp_f32_e32 v102, v102
	v_exp_f32_e32 v103, v103
	v_add_f32_e32 v233, v233, v102
	v_add_f32_e32 v233, v233, v103
	s_setprio 1
	s_waitcnt lgkmcnt(4)
	v_mfma_f32_32x32x16_bf16 v[48:63], v[160:163], v[152:155], v[48:63]
	ds_read_b128 v[76:79], v234 offset:44128
	v_cvt_pk_bf16_f32 v144, v96, v97
	v_cvt_pk_bf16_f32 v145, v98, v99
	v_cvt_pk_bf16_f32 v146, v100, v101
	v_cvt_pk_bf16_f32 v147, v102, v103
	v_add_f32_e32 v255, 0x43000000, v237
	v_fma_f32 v254, v236, v255, v253
	s_waitcnt lgkmcnt(4)
	v_mfma_f32_32x32x16_bf16 v[48:63], v[244:247], v[156:159], v[48:63]
	ds_read_b128 v[160:163], v234 offset:48704
	v_exp_f32_e32 v104, v104
	v_exp_f32_e32 v105, v105
	v_add_f32_e32 v233, v233, v104
	v_add_f32_e32 v233, v233, v105
	v_fmamk_f32 v96, v201, 0x00000000, v254
	v_fmamk_f32 v97, v201, 0x3f800000, v254
	s_waitcnt lgkmcnt(4)
	v_mfma_f32_32x32x16_bf16 v[32:47], v[64:67], v[152:155], v[32:47]
	ds_read_b128 v[244:247], v234 offset:48736
	v_exp_f32_e32 v106, v106
	v_exp_f32_e32 v107, v107
	v_add_f32_e32 v233, v233, v106
	v_add_f32_e32 v233, v233, v107
	v_fmamk_f32 v98, v201, 0x40000000, v254
	v_fmamk_f32 v99, v201, 0x40400000, v254
	s_waitcnt lgkmcnt(4)
	v_mfma_f32_32x32x16_bf16 v[32:47], v[68:71], v[156:159], v[32:47]
	v_exp_f32_e32 v108, v108
	v_exp_f32_e32 v109, v109
	v_add_f32_e32 v233, v233, v108
	v_add_f32_e32 v233, v233, v109
	v_fmamk_f32 v100, v201, 0x40800000, v254
	v_fmamk_f32 v101, v201, 0x40a00000, v254
	s_setprio 0
	s_waitcnt lgkmcnt(3)
	v_mfma_f32_32x32x16_bf16 v[16:31], v[72:75], v[152:155], v[16:31]
	v_exp_f32_e32 v110, v110
	v_exp_f32_e32 v111, v111
	v_add_f32_e32 v233, v233, v110
	v_add_f32_e32 v233, v233, v111
	v_fmamk_f32 v102, v201, 0x40c00000, v254
	v_fmamk_f32 v103, v201, 0x40e00000, v254
	s_waitcnt lgkmcnt(2)
	v_mfma_f32_32x32x16_bf16 v[16:31], v[76:79], v[156:159], v[16:31]
	v_cvt_pk_bf16_f32 v148, v104, v105
	v_cvt_pk_bf16_f32 v149, v106, v107
	v_cvt_pk_bf16_f32 v150, v108, v109
	v_cvt_pk_bf16_f32 v151, v110, v111
	s_waitcnt lgkmcnt(1)
	v_mfma_f32_32x32x16_bf16 v[0:15], v[160:163], v[152:155], v[0:15]
	v_fmamk_f32 v104, v201, 0x41800000, v254
	v_fmamk_f32 v105, v201, 0x41880000, v254
	v_fmamk_f32 v106, v201, 0x41900000, v254
	v_fmamk_f32 v107, v201, 0x41980000, v254
	v_add_f32_e32 v233, v233, v238
	s_waitcnt lgkmcnt(0)
	v_mfma_f32_32x32x16_bf16 v[0:15], v[244:247], v[156:159], v[0:15]
	v_fmamk_f32 v108, v201, 0x41a00000, v254
	v_fmamk_f32 v109, v201, 0x41a80000, v254
	v_fmamk_f32 v110, v201, 0x41b00000, v254
	v_fmamk_f32 v111, v201, 0x41b80000, v254
	s_cmp_lt_u32 s90, 1
	s_cbranch_scc1 .LfixB_skip_h0_do
	s_cmp_lt_i32 s87, s38
	s_cbranch_scc1 .LfixB_skip_h0

.Lan_331_h1:
	v_cvt_f32_i32_e32 v237, v231
	s_setprio 0
	s_waitcnt lgkmcnt(4)
	v_mfma_f32_32x32x16_bf16 v[96:111], v[64:67], v[112:115], v[96:111]
	ds_read_b128 v[244:247], v234 offset:34848
	v_exp_f32_e32 v80, v80
	v_exp_f32_e32 v81, v81
	v_add_f32_e32 v238, 0, v80
	v_add_f32_e32 v238, v238, v81
	s_waitcnt lgkmcnt(4)
	v_mfma_f32_32x32x16_bf16 v[96:111], v[68:71], v[116:119], v[96:111]
	ds_read_b128 v[64:67], v234 offset:39424
	v_exp_f32_e32 v82, v82
	v_exp_f32_e32 v83, v83
	v_add_f32_e32 v238, v238, v82
	v_add_f32_e32 v238, v238, v83
	s_waitcnt lgkmcnt(4)
	v_mfma_f32_32x32x16_bf16 v[96:111], v[72:75], v[120:123], v[96:111]
	ds_read_b128 v[68:71], v234 offset:39456
	v_exp_f32_e32 v84, v84
	v_exp_f32_e32 v85, v85
	v_add_f32_e32 v238, v238, v84
	v_add_f32_e32 v238, v238, v85
	s_waitcnt lgkmcnt(4)
	v_mfma_f32_32x32x16_bf16 v[96:111], v[76:79], v[124:127], v[96:111]
	ds_read_b128 v[72:75], v234 offset:44032
	v_exp_f32_e32 v86, v86
	v_exp_f32_e32 v87, v87
	v_add_f32_e32 v238, v238, v86
	v_add_f32_e32 v238, v238, v87
	s_setprio 1
	s_waitcnt lgkmcnt(4)
	v_mfma_f32_32x32x16_bf16 v[48:63], v[160:163], v[144:147], v[48:63]
	ds_read_b128 v[76:79], v234 offset:44064
	v_cvt_pk_bf16_f32 v152, v80, v81
	v_cvt_pk_bf16_f32 v153, v82, v83
	v_cvt_pk_bf16_f32 v154, v84, v85
	v_cvt_pk_bf16_f32 v155, v86, v87
	v_add_f32_e32 v255, 0x42800000, v237
	v_fma_f32 v254, v236, v255, v253
	s_waitcnt lgkmcnt(4)
	v_mfma_f32_32x32x16_bf16 v[48:63], v[244:247], v[148:151], v[48:63]
	ds_read_b128 v[160:163], v234 offset:48640
	v_exp_f32_e32 v88, v88
	v_exp_f32_e32 v89, v89
	v_add_f32_e32 v238, v238, v88
	v_add_f32_e32 v238, v238, v89
	v_fmamk_f32 v80, v201, 0x42000000, v254
	v_fmamk_f32 v81, v201, 0x42040000, v254
	s_waitcnt lgkmcnt(4)
	v_mfma_f32_32x32x16_bf16 v[32:47], v[64:67], v[144:147], v[32:47]
	ds_read_b128 v[244:247], v234 offset:48672
	v_exp_f32_e32 v90, v90
	v_exp_f32_e32 v91, v91
	v_add_f32_e32 v238, v238, v90
	v_add_f32_e32 v238, v238, v91
	v_fmamk_f32 v82, v201, 0x42080000, v254
	v_fmamk_f32 v83, v201, 0x420c0000, v254
	s_waitcnt lgkmcnt(4)
	v_mfma_f32_32x32x16_bf16 v[32:47], v[68:71], v[148:151], v[32:47]
	ds_read_b128 v[64:67], v235 offset:8704
	v_exp_f32_e32 v92, v92
	v_exp_f32_e32 v93, v93
	v_add_f32_e32 v238, v238, v92
	v_add_f32_e32 v238, v238, v93
	v_fmamk_f32 v84, v201, 0x42100000, v254
	v_fmamk_f32 v85, v201, 0x42140000, v254
	s_setprio 0
	s_waitcnt lgkmcnt(4)
	v_mfma_f32_32x32x16_bf16 v[16:31], v[72:75], v[144:147], v[16:31]
	ds_read_b128 v[68:71], v235 offset:8736
	v_exp_f32_e32 v94, v94
	v_exp_f32_e32 v95, v95
	v_add_f32_e32 v238, v238, v94
	v_add_f32_e32 v238, v238, v95
	v_fmamk_f32 v86, v201, 0x42180000, v254
	v_fmamk_f32 v87, v201, 0x421c0000, v254
	s_waitcnt lgkmcnt(4)
	v_mfma_f32_32x32x16_bf16 v[16:31], v[76:79], v[148:151], v[16:31]
	ds_read_b128 v[72:75], v235 offset:8768
	v_cvt_pk_bf16_f32 v156, v88, v89
	v_cvt_pk_bf16_f32 v157, v90, v91
	v_cvt_pk_bf16_f32 v158, v92, v93
	v_cvt_pk_bf16_f32 v159, v94, v95
	s_waitcnt lgkmcnt(4)
	v_mfma_f32_32x32x16_bf16 v[0:15], v[160:163], v[144:147], v[0:15]
	ds_read_b128 v[76:79], v235 offset:8800
	v_fmamk_f32 v88, v201, 0x42400000, v254
	v_fmamk_f32 v89, v201, 0x42440000, v254
	v_fmamk_f32 v90, v201, 0x42480000, v254
	v_fmamk_f32 v91, v201, 0x424c0000, v254
	v_add_f32_e32 v238, v238, v233
	s_waitcnt lgkmcnt(4)
	v_mfma_f32_32x32x16_bf16 v[0:15], v[244:247], v[148:151], v[0:15]
	ds_read_b128 v[160:163], v234 offset:34880
	v_fmamk_f32 v92, v201, 0x42500000, v254
	v_fmamk_f32 v93, v201, 0x42540000, v254
	v_fmamk_f32 v94, v201, 0x42580000, v254
	v_fmamk_f32 v95, v201, 0x425c0000, v254
	s_cmp_lt_u32 s90, 2
	s_cbranch_scc1 .LfixA_skip_h1_do
	s_cmp_lt_i32 s90, s38
	s_cbranch_scc1 .LfixA_skip_h1

.LfixA_skip_h1:
	s_setprio 1
	s_waitcnt lgkmcnt(4)
	v_mfma_f32_32x32x16_bf16 v[80:95], v[64:67], v[112:115], v[80:95]
	ds_read_b128 v[244:247], v234 offset:34912
	v_exp_f32_e32 v96, v96
	v_exp_f32_e32 v97, v97
	v_add_f32_e32 v233, 0, v96
	v_add_f32_e32 v233, v233, v97
	s_waitcnt lgkmcnt(4)
	v_mfma_f32_32x32x16_bf16 v[80:95], v[68:71], v[116:119], v[80:95]
	ds_read_b128 v[64:67], v234 offset:39488
	v_exp_f32_e32 v98, v98
	v_exp_f32_e32 v99, v99
	v_add_f32_e32 v233, v233, v98
	v_add_f32_e32 v233, v233, v99
	s_waitcnt lgkmcnt(4)
	v_mfma_f32_32x32x16_bf16 v[80:95], v[72:75], v[120:123], v[80:95]
	ds_read_b128 v[68:71], v234 offset:39520
	v_exp_f32_e32 v100, v100
	v_exp_f32_e32 v101, v101
	v_add_f32_e32 v233, v233, v100
	v_add_f32_e32 v233, v233, v101
	s_waitcnt lgkmcnt(4)
	v_mfma_f32_32x32x16_bf16 v[80:95], v[76:79], v[124:127], v[80:95]
	ds_read_b128 v[72:75], v234 offset:44096
	v_exp_f32_e32 v102, v102
	v_exp_f32_e32 v103, v103
	v_add_f32_e32 v233, v233, v102
	v_add_f32_e32 v233, v233, v103
	s_setprio 0
	s_waitcnt lgkmcnt(4)
	v_mfma_f32_32x32x16_bf16 v[48:63], v[160:163], v[152:155], v[48:63]
	ds_read_b128 v[76:79], v234 offset:44128
	v_cvt_pk_bf16_f32 v144, v96, v97
	v_cvt_pk_bf16_f32 v145, v98, v99
	v_cvt_pk_bf16_f32 v146, v100, v101
	v_cvt_pk_bf16_f32 v147, v102, v103
	v_add_f32_e32 v255, 0x43000000, v237
	v_fma_f32 v254, v236, v255, v253
	s_waitcnt lgkmcnt(4)
	v_mfma_f32_32x32x16_bf16 v[48:63], v[244:247], v[156:159], v[48:63]
	ds_read_b128 v[160:163], v234 offset:48704
	v_exp_f32_e32 v104, v104
	v_exp_f32_e32 v105, v105
	v_add_f32_e32 v233, v233, v104
	v_add_f32_e32 v233, v233, v105
	v_fmamk_f32 v96, v201, 0x00000000, v254
	v_fmamk_f32 v97, v201, 0x3f800000, v254
	s_waitcnt lgkmcnt(4)
	v_mfma_f32_32x32x16_bf16 v[32:47], v[64:67], v[152:155], v[32:47]
	ds_read_b128 v[244:247], v234 offset:48736
	v_exp_f32_e32 v106, v106
	v_exp_f32_e32 v107, v107
	v_add_f32_e32 v233, v233, v106
	v_add_f32_e32 v233, v233, v107
	v_fmamk_f32 v98, v201, 0x40000000, v254
	v_fmamk_f32 v99, v201, 0x40400000, v254
	s_waitcnt lgkmcnt(4)
	v_mfma_f32_32x32x16_bf16 v[32:47], v[68:71], v[156:159], v[32:47]
	v_exp_f32_e32 v108, v108
	v_exp_f32_e32 v109, v109
	v_add_f32_e32 v233, v233, v108
	v_add_f32_e32 v233, v233, v109
	v_fmamk_f32 v100, v201, 0x40800000, v254
	v_fmamk_f32 v101, v201, 0x40a00000, v254
	s_setprio 1
	s_waitcnt lgkmcnt(3)
	v_mfma_f32_32x32x16_bf16 v[16:31], v[72:75], v[152:155], v[16:31]
	v_exp_f32_e32 v110, v110
	v_exp_f32_e32 v111, v111
	v_add_f32_e32 v233, v233, v110
	v_add_f32_e32 v233, v233, v111
	v_fmamk_f32 v102, v201, 0x40c00000, v254
	v_fmamk_f32 v103, v201, 0x40e00000, v254
	s_waitcnt lgkmcnt(2)
	v_mfma_f32_32x32x16_bf16 v[16:31], v[76:79], v[156:159], v[16:31]
	v_cvt_pk_bf16_f32 v148, v104, v105
	v_cvt_pk_bf16_f32 v149, v106, v107
	v_cvt_pk_bf16_f32 v150, v108, v109
	v_cvt_pk_bf16_f32 v151, v110, v111
	s_waitcnt lgkmcnt(1)
	v_mfma_f32_32x32x16_bf16 v[0:15], v[160:163], v[152:155], v[0:15]
	v_fmamk_f32 v104, v201, 0x41800000, v254
	v_fmamk_f32 v105, v201, 0x41880000, v254
	v_fmamk_f32 v106, v201, 0x41900000, v254
	v_fmamk_f32 v107, v201, 0x41980000, v254
	v_add_f32_e32 v233, v233, v238
	s_waitcnt lgkmcnt(0)
	v_mfma_f32_32x32x16_bf16 v[0:15], v[244:247], v[156:159], v[0:15]
	v_fmamk_f32 v108, v201, 0x41a00000, v254
	v_fmamk_f32 v109, v201, 0x41a80000, v254
	v_fmamk_f32 v110, v201, 0x41b00000, v254
	v_fmamk_f32 v111, v201, 0x41b80000, v254
	s_cmp_lt_u32 s90, 1
	s_cbranch_scc1 .LfixB_skip_h1_do
	s_cmp_lt_i32 s87, s38
	s_cbranch_scc1 .LfixB_skip_h1
